# P2d unit loop software-pipelined: next unit's 16 loads in flight during the current unit, LDS tile double-buffered (one barrier per unit); 16-byte pad keeps later code at previous mod-64 placement
# speedup vs baseline: 1.1065x; 1.0031x over previous
; #define LAS __attribute__((address_space(3)))
; DI int rot_t(int c, int t) { return (t + 128 * c) & (MTOK - 1); }
; DI void p2d_unit(const Frame& F, int unit, const bf16* HY, const bf16* YT, bf16* YH, const float* cw, const float* cb) {
;     const int tt = unit >> 3, cgp = unit & 7;
;     LAS unsigned char* T = F.lds;
;     const int t0 = F.tid >> 3, cc = (F.tid & 7) * 8, c0 = cgp * 64 + cc;
;     u32x4 xa[2], xb[2], xc[2];
; #pragma unroll
;     for (int j = 0; j < 2; ++j) { const int tok = tt * 128 + t0 + 64 * j; bool hp, hn; tok_edges(tok, hp, hn); conv3_load(HY, tok, c0, hp, hn, xa[j], xb[j], xc[j]); }
;     { const int c = F.tid >> 3, cg = cgp * 64 + c;
; #pragma unroll
;       for (int j = 0; j < 2; ++j) { const int tch = (F.tid & 7) * 8 + 64 * j;
;           *(LAS u32x4*)(T + c * TR_ROW + tch * 2) = *(const u32x4*)(YT + (size_t)cg * MTOK + rot_t(cg, tt * 128 + tch)); } }
; __global__ void __launch_bounds__(512, 2) hybrid_fwd(Args args) {
;     ...
;     DUP_BEGIN(4) if (IN(4)) { for (int u = F.bid; u < 2048; u += F.G) p2d_unit(F, u, HY, UT, Kb, args.in[5], args.in[6]); }
.LBB0_1164:
	s_cmp_lt_i32 s84, 5
	s_cselect_b64 s[2:3], -1, 0
	s_and_b64 s[2:3], s[2:3], s[0:1]
	v_readlane_b32 s0, v246, 32
	v_readlane_b32 s1, v246, 33
	s_and_b64 s[0:1], s[2:3], s[0:1]
	s_andn2_b64 vcc, exec, s[0:1]
	s_cbranch_vccnz .LBB0_1175
	v_lshrrev_b32_e32 v34, 3, v150
	v_and_b32_e32 v35, 56, v152
	s_movk_i32 s0, 0x110
	s_add_u32 s4, s74, 0x1800
	s_waitcnt vmcnt(1)
	v_mad_u32_u24 v36, v34, s0, 0
	v_lshlrev_b32_e32 v37, 1, v35
	s_addc_u32 s5, s75, 0
	s_movk_i32 s0, 0xfef2
	v_add_u32_e32 v38, 64, v34
	v_or_b32_e32 v0, 0x80, v37
	s_add_u32 s6, s74, 0x3000
	v_mul_u32_u24_e32 v1, 0x110, v35
	v_mad_i32_i24 v2, v34, s0, v36
	v_lshl_add_u32 v3, v38, 1, 0
	s_addc_u32 s7, s75, 0
	s_lshl_b32 s10, s33, 6
	s_lshl_b32 s11, s89, 6
	v_mov_b32_e32 v25, 0
	s_movk_i32 s12, 0x4000
	v_mov_b32_e32 v39, 0xfff
	s_movk_i32 s13, 0xc00
	v_mov_b32_e32 v40, 0x3fff
	s_movk_i32 s14, 0x3fc0
	s_movk_i32 s15, 0x7f80
	v_add_u32_e32 v41, v36, v0
	v_add_u32_e32 v42, v2, v1
	v_add_u32_e32 v43, v3, v1
	v_add_u32_e32 v44, v36, v37
	s_mov_b32 s16, s33
	v_mov_b32_e32 v25, 0
	s_and_b32 s19, s10, 0x1c0
	s_ashr_i32 s18, s16, 3
	v_or_b32_e32 v30, s19, v35
	s_lshl_b32 s17, s18, 7
	v_lshlrev_b32_e32 v24, 1, v30
	v_or_b32_e32 v26, s17, v34
	v_add_u32_e32 v31, s19, v34
	v_lshlrev_b32_e32 v28, 16, v31
	v_add_lshl_u32 v31, v31, s18, 7
	v_mov_b32_e32 v29, v25
	v_and_or_b32 v31, v31, s15, v35
	v_lshl_add_u64 v[28:29], s[60:61], 0, v[28:29]
	v_lshlrev_b32_e32 v32, 1, v31
	v_mov_b32_e32 v33, v25
	v_lshl_add_u64 v[28:29], v[28:29], 0, v[32:33]
	global_load_dwordx4 v[48:51], v[28:29], off
	global_load_dwordx4 v[52:55], v[28:29], off offset:128
	v_lshl_add_u64 v[2:3], s[80:81], 0, v[24:25]
	v_mad_i64_i32 v[4:5], s[0:1], v26, s13, v[2:3]
	global_load_dwordx4 v[56:59], v[4:5], off
	v_bitop3_b32 v0, s17, v39, v34 bitop3:0xc8
	v_add_u32_e32 v1, 0xffffc000, v26
	v_cmp_gt_i32_e32 vcc, s12, v26
	v_mov_b32_e32 v60, 0
	v_mov_b32_e32 v61, 0
	v_mov_b32_e32 v62, 0
	v_mov_b32_e32 v63, 0
	v_cndmask_b32_e32 v0, v1, v0, vcc
	v_cmp_ne_u32_e64 s[0:1], 0, v0
	v_mov_b32_e32 v64, 0
	v_mov_b32_e32 v65, 0
	v_mov_b32_e32 v66, 0
	v_mov_b32_e32 v67, 0
	s_and_saveexec_b64 s[8:9], s[0:1]
	global_load_dwordx4 v[60:63], v[4:5], off offset:-3072
	s_or_b64 exec, exec, s[8:9]
	v_cndmask_b32_e32 v1, v40, v39, vcc
	v_cmp_lt_u32_e32 vcc, v0, v1
	s_and_saveexec_b64 s[0:1], vcc
	global_load_dwordx4 v[64:67], v[4:5], off offset:3072
	s_or_b64 exec, exec, s[0:1]
	v_add_u32_e32 v1, 64, v26
	v_mad_i64_i32 v[28:29], s[0:1], v1, s13, v[2:3]
	global_load_dwordx4 v[68:71], v[28:29], off
	v_and_b32_e32 v1, 0xfff, v1
	v_add_u32_e32 v2, 0xffffc040, v26
	v_cmp_gt_i32_e32 vcc, s14, v26
	v_mov_b32_e32 v72, 0
	v_mov_b32_e32 v73, 0
	v_mov_b32_e32 v74, 0
	v_mov_b32_e32 v75, 0
	v_cndmask_b32_e32 v8, v2, v1, vcc
	v_cmp_ne_u32_e64 s[0:1], 0, v8
	v_mov_b32_e32 v76, 0
	v_mov_b32_e32 v77, 0
	v_mov_b32_e32 v78, 0
	v_mov_b32_e32 v79, 0
	s_and_saveexec_b64 s[8:9], s[0:1]
	global_load_dwordx4 v[72:75], v[28:29], off offset:-3072
	s_or_b64 exec, exec, s[8:9]
	v_cndmask_b32_e32 v9, v40, v39, vcc
	v_cmp_lt_u32_e32 vcc, v8, v9
	s_and_saveexec_b64 s[0:1], vcc
	global_load_dwordx4 v[76:79], v[28:29], off offset:3072
	s_or_b64 exec, exec, s[0:1]
	v_lshlrev_b32_e32 v12, 2, v30
	v_lshl_add_u64 v[6:7], s[58:59], 0, v[24:25]
	v_ashrrev_i32_e32 v27, 31, v26
	global_load_dwordx4 v[80:83], v12, s[4:5] offset:16
	global_load_dwordx4 v[84:87], v12, s[4:5]
	global_load_dwordx4 v[88:91], v12, s[74:75]
	global_load_dwordx4 v[92:95], v12, s[74:75] offset:16
	global_load_dwordx4 v[96:99], v12, s[6:7] offset:16
	global_load_dwordx4 v[100:103], v12, s[6:7]
	global_load_dwordx4 v[104:107], v12, s[76:77]
	global_load_dwordx4 v[108:111], v12, s[76:77] offset:16
	v_lshlrev_b64 v[8:9], 10, v[26:27]
	v_lshl_add_u64 v[112:113], v[6:7], 0, v[8:9]
	v_add_u32_e32 v10, s17, v38
	v_ashrrev_i32_e32 v11, 31, v10
	v_lshlrev_b64 v[10:11], 10, v[10:11]
	v_lshl_add_u64 v[114:115], v[6:7], 0, v[10:11]
.Lp2d_loop:
	s_add_i32 s20, s16, s89
	s_add_i32 s21, s10, s11
	s_cmpk_lt_i32 s20, 0x800
	s_cbranch_scc0 .Lp2d_lastA
	v_mov_b32_e32 v25, 0
	s_and_b32 s19, s21, 0x1c0
	s_ashr_i32 s18, s20, 3
	v_or_b32_e32 v30, s19, v35
	s_lshl_b32 s17, s18, 7
	v_lshlrev_b32_e32 v24, 1, v30
	v_or_b32_e32 v26, s17, v34
	v_add_u32_e32 v31, s19, v34
	v_lshlrev_b32_e32 v28, 16, v31
	v_add_lshl_u32 v31, v31, s18, 7
	v_mov_b32_e32 v29, v25
	v_and_or_b32 v31, v31, s15, v35
	v_lshl_add_u64 v[28:29], s[60:61], 0, v[28:29]
	v_lshlrev_b32_e32 v32, 1, v31
	v_mov_b32_e32 v33, v25
	v_lshl_add_u64 v[28:29], v[28:29], 0, v[32:33]
	global_load_dwordx4 v[170:173], v[28:29], off
	global_load_dwordx4 v[174:177], v[28:29], off offset:128
	v_lshl_add_u64 v[2:3], s[80:81], 0, v[24:25]
	v_mad_i64_i32 v[4:5], s[0:1], v26, s13, v[2:3]
	global_load_dwordx4 v[178:181], v[4:5], off
	v_bitop3_b32 v0, s17, v39, v34 bitop3:0xc8
	v_add_u32_e32 v1, 0xffffc000, v26
	v_cmp_gt_i32_e32 vcc, s12, v26
	v_mov_b32_e32 v182, 0
	v_mov_b32_e32 v183, 0
	v_mov_b32_e32 v184, 0
	v_mov_b32_e32 v185, 0
	v_cndmask_b32_e32 v0, v1, v0, vcc
	v_cmp_ne_u32_e64 s[0:1], 0, v0
	v_mov_b32_e32 v186, 0
	v_mov_b32_e32 v187, 0
	v_mov_b32_e32 v188, 0
	v_mov_b32_e32 v189, 0
	s_and_saveexec_b64 s[8:9], s[0:1]
	global_load_dwordx4 v[182:185], v[4:5], off offset:-3072
	s_or_b64 exec, exec, s[8:9]
	v_cndmask_b32_e32 v1, v40, v39, vcc
	v_cmp_lt_u32_e32 vcc, v0, v1
	s_and_saveexec_b64 s[0:1], vcc
	global_load_dwordx4 v[186:189], v[4:5], off offset:3072
	s_or_b64 exec, exec, s[0:1]
	v_add_u32_e32 v1, 64, v26
	v_mad_i64_i32 v[28:29], s[0:1], v1, s13, v[2:3]
	global_load_dwordx4 v[190:193], v[28:29], off
	v_and_b32_e32 v1, 0xfff, v1
	v_add_u32_e32 v2, 0xffffc040, v26
	v_cmp_gt_i32_e32 vcc, s14, v26
	v_mov_b32_e32 v194, 0
	v_mov_b32_e32 v195, 0
	v_mov_b32_e32 v196, 0
	v_mov_b32_e32 v197, 0
	v_cndmask_b32_e32 v8, v2, v1, vcc
	v_cmp_ne_u32_e64 s[0:1], 0, v8
	v_mov_b32_e32 v198, 0
	v_mov_b32_e32 v199, 0
	v_mov_b32_e32 v200, 0
	v_mov_b32_e32 v201, 0
	s_and_saveexec_b64 s[8:9], s[0:1]
	global_load_dwordx4 v[194:197], v[28:29], off offset:-3072
	s_or_b64 exec, exec, s[8:9]
	v_cndmask_b32_e32 v9, v40, v39, vcc
	v_cmp_lt_u32_e32 vcc, v8, v9
	s_and_saveexec_b64 s[0:1], vcc
	global_load_dwordx4 v[198:201], v[28:29], off offset:3072
	s_or_b64 exec, exec, s[0:1]
	v_lshlrev_b32_e32 v12, 2, v30
	v_lshl_add_u64 v[6:7], s[58:59], 0, v[24:25]
	v_ashrrev_i32_e32 v27, 31, v26
	global_load_dwordx4 v[202:205], v12, s[4:5] offset:16
	global_load_dwordx4 v[206:209], v12, s[4:5]
	global_load_dwordx4 v[210:213], v12, s[74:75]
	global_load_dwordx4 v[214:217], v12, s[74:75] offset:16
	global_load_dwordx4 v[218:221], v12, s[6:7] offset:16
	global_load_dwordx4 v[222:225], v12, s[6:7]
	global_load_dwordx4 v[226:229], v12, s[76:77]
	global_load_dwordx4 v[230:233], v12, s[76:77] offset:16
	v_lshlrev_b64 v[8:9], 10, v[26:27]
	v_lshl_add_u64 v[116:117], v[6:7], 0, v[8:9]
	v_add_u32_e32 v10, s17, v38
	v_ashrrev_i32_e32 v11, 31, v10
	v_lshlrev_b64 v[10:11], 10, v[10:11]
	v_lshl_add_u64 v[118:119], v[6:7], 0, v[10:11]
	s_waitcnt vmcnt(30)
; #define LAS __attribute__((address_space(3)))
; DI unsigned pk2(float lo, float hi) { f32x2_t v = {lo, hi}; bf16x2_t b = __builtin_convertvector(v, bf16x2_t); return __builtin_bit_cast(unsigned, b); }
; DI int rot_t(int c, int t) { return (t + 128 * c) & (MTOK - 1); }
; DI void p2d_unit(const Frame& F, int unit, const bf16* HY, const bf16* YT, bf16* YH, const float* cw, const float* cb) {
;     ...
;     { const int c = F.tid >> 3, cg = cgp * 64 + c;
; #pragma unroll
;       for (int j = 0; j < 2; ++j) { const int tch = (F.tid & 7) * 8 + 64 * j;
;           *(LAS u32x4*)(T + c * TR_ROW + tch * 2) = *(const u32x4*)(YT + (size_t)cg * MTOK + rot_t(cg, tt * 128 + tch)); } }
;     __syncthreads();
;     { ConvW W0; conv3_w(W0, cw, cb, c0);
; #pragma unroll
;       for (int j = 0; j < 2; ++j) { const int t = t0 + 64 * j, tok = tt * 128 + t; float x0[8], y[8]; conv3_do(W0, xa[j], xb[j], xc[j], x0);
; #pragma unroll
;           for (int e = 0; e < 8; ++e) y[e] = __uint_as_float((unsigned)(*(const LAS bf16*)(T + (cc + e) * TR_ROW + t * 2)) << 16) * x0[e];
;           u32x4 w; w.x = pk2(y[0], y[1]); w.y = pk2(y[2], y[3]); w.z = pk2(y[4], y[5]); w.w = pk2(y[6], y[7]);
;           *(u32x4*)(YH + (size_t)tok * 512 + c0) = w; } }
;     __syncthreads();
	ds_write_b128 v44, v[48:51]
	ds_write_b128 v41, v[52:55]
	s_waitcnt lgkmcnt(0)
	s_barrier
	ds_read_u16 v14, v42
	ds_read_u16 v15, v42 offset:272
	ds_read_u16 v16, v42 offset:544
	ds_read_u16 v17, v42 offset:816
	ds_read_u16 v18, v42 offset:1088
	ds_read_u16 v19, v42 offset:1360
	ds_read_u16 v20, v42 offset:1632
	ds_read_u16 v21, v42 offset:1904
	ds_read_u16 v22, v43
	ds_read_u16 v23, v43 offset:272
	ds_read_u16 v24, v43 offset:544
	ds_read_u16 v25, v43 offset:816
	ds_read_u16 v26, v43 offset:1088
	ds_read_u16 v27, v43 offset:1360
	ds_read_u16 v28, v43 offset:1632
	ds_read_u16 v29, v43 offset:1904
	s_waitcnt vmcnt(16)
	v_lshlrev_b32_e32 v0, 16, v56
	v_and_b32_e32 v1, 0xffff0000, v56
	v_lshlrev_b32_e32 v2, 16, v60
	v_and_b32_e32 v3, 0xffff0000, v60
	v_lshlrev_b32_e32 v4, 16, v64
	v_and_b32_e32 v5, 0xffff0000, v64
	v_pk_mul_f32 v[6:7], v[84:85], v[0:1]
	v_pk_fma_f32 v[6:7], v[88:89], v[2:3], v[6:7]
	v_pk_fma_f32 v[6:7], v[100:101], v[4:5], v[6:7]
	v_pk_add_f32 v[6:7], v[104:105], v[6:7]
	s_waitcnt lgkmcnt(0)
	v_lshlrev_b32_e32 v8, 16, v14
	v_lshlrev_b32_e32 v9, 16, v15
	v_pk_mul_f32 v[6:7], v[6:7], v[8:9]
	v_cvt_pk_bf16_f32 v120, v6, v7
	v_lshlrev_b32_e32 v0, 16, v57
	v_and_b32_e32 v1, 0xffff0000, v57
	v_lshlrev_b32_e32 v2, 16, v61
	v_and_b32_e32 v3, 0xffff0000, v61
	v_lshlrev_b32_e32 v4, 16, v65
	v_and_b32_e32 v5, 0xffff0000, v65
	v_pk_mul_f32 v[6:7], v[86:87], v[0:1]
	v_pk_fma_f32 v[6:7], v[90:91], v[2:3], v[6:7]
	v_pk_fma_f32 v[6:7], v[102:103], v[4:5], v[6:7]
	v_pk_add_f32 v[6:7], v[106:107], v[6:7]
	v_lshlrev_b32_e32 v8, 16, v16
	v_lshlrev_b32_e32 v9, 16, v17
	v_pk_mul_f32 v[6:7], v[6:7], v[8:9]
	v_cvt_pk_bf16_f32 v121, v6, v7
	v_lshlrev_b32_e32 v0, 16, v58
	v_and_b32_e32 v1, 0xffff0000, v58
	v_lshlrev_b32_e32 v2, 16, v62
	v_and_b32_e32 v3, 0xffff0000, v62
	v_lshlrev_b32_e32 v4, 16, v66
	v_and_b32_e32 v5, 0xffff0000, v66
	v_pk_mul_f32 v[6:7], v[80:81], v[0:1]
	v_pk_fma_f32 v[6:7], v[92:93], v[2:3], v[6:7]
	v_pk_fma_f32 v[6:7], v[96:97], v[4:5], v[6:7]
	v_pk_add_f32 v[6:7], v[108:109], v[6:7]
	v_lshlrev_b32_e32 v8, 16, v18
	v_lshlrev_b32_e32 v9, 16, v19
	v_pk_mul_f32 v[6:7], v[6:7], v[8:9]
	v_cvt_pk_bf16_f32 v122, v6, v7
	v_lshlrev_b32_e32 v0, 16, v59
	v_and_b32_e32 v1, 0xffff0000, v59
	v_lshlrev_b32_e32 v2, 16, v63
	v_and_b32_e32 v3, 0xffff0000, v63
	v_lshlrev_b32_e32 v4, 16, v67
	v_and_b32_e32 v5, 0xffff0000, v67
	v_pk_mul_f32 v[6:7], v[82:83], v[0:1]
	v_pk_fma_f32 v[6:7], v[94:95], v[2:3], v[6:7]
	v_pk_fma_f32 v[6:7], v[98:99], v[4:5], v[6:7]
	v_pk_add_f32 v[6:7], v[110:111], v[6:7]
	v_lshlrev_b32_e32 v8, 16, v20
	v_lshlrev_b32_e32 v9, 16, v21
	v_pk_mul_f32 v[6:7], v[6:7], v[8:9]
	v_cvt_pk_bf16_f32 v123, v6, v7
	v_lshlrev_b32_e32 v0, 16, v68
	v_and_b32_e32 v1, 0xffff0000, v68
	v_lshlrev_b32_e32 v2, 16, v72
	v_and_b32_e32 v3, 0xffff0000, v72
	v_lshlrev_b32_e32 v4, 16, v76
	v_and_b32_e32 v5, 0xffff0000, v76
	v_pk_mul_f32 v[6:7], v[84:85], v[0:1]
	v_pk_fma_f32 v[6:7], v[88:89], v[2:3], v[6:7]
	v_pk_fma_f32 v[6:7], v[100:101], v[4:5], v[6:7]
	v_pk_add_f32 v[6:7], v[104:105], v[6:7]
	v_lshlrev_b32_e32 v8, 16, v22
	v_lshlrev_b32_e32 v9, 16, v23
	v_pk_mul_f32 v[6:7], v[6:7], v[8:9]
	v_cvt_pk_bf16_f32 v124, v6, v7
	v_lshlrev_b32_e32 v0, 16, v69
	v_and_b32_e32 v1, 0xffff0000, v69
	v_lshlrev_b32_e32 v2, 16, v73
	v_and_b32_e32 v3, 0xffff0000, v73
	v_lshlrev_b32_e32 v4, 16, v77
	v_and_b32_e32 v5, 0xffff0000, v77
	v_pk_mul_f32 v[6:7], v[86:87], v[0:1]
	v_pk_fma_f32 v[6:7], v[90:91], v[2:3], v[6:7]
	v_pk_fma_f32 v[6:7], v[102:103], v[4:5], v[6:7]
	v_pk_add_f32 v[6:7], v[106:107], v[6:7]
	v_lshlrev_b32_e32 v8, 16, v24
	v_lshlrev_b32_e32 v9, 16, v25
	v_pk_mul_f32 v[6:7], v[6:7], v[8:9]
	v_cvt_pk_bf16_f32 v125, v6, v7
	v_lshlrev_b32_e32 v0, 16, v70
	v_and_b32_e32 v1, 0xffff0000, v70
	v_lshlrev_b32_e32 v2, 16, v74
	v_and_b32_e32 v3, 0xffff0000, v74
	v_lshlrev_b32_e32 v4, 16, v78
	v_and_b32_e32 v5, 0xffff0000, v78
	v_pk_mul_f32 v[6:7], v[80:81], v[0:1]
	v_pk_fma_f32 v[6:7], v[92:93], v[2:3], v[6:7]
	v_pk_fma_f32 v[6:7], v[96:97], v[4:5], v[6:7]
	v_pk_add_f32 v[6:7], v[108:109], v[6:7]
	v_lshlrev_b32_e32 v8, 16, v26
	v_lshlrev_b32_e32 v9, 16, v27
	v_pk_mul_f32 v[6:7], v[6:7], v[8:9]
	v_cvt_pk_bf16_f32 v126, v6, v7
	v_lshlrev_b32_e32 v0, 16, v71
	v_and_b32_e32 v1, 0xffff0000, v71
	v_lshlrev_b32_e32 v2, 16, v75
	v_and_b32_e32 v3, 0xffff0000, v75
	v_lshlrev_b32_e32 v4, 16, v79
	v_and_b32_e32 v5, 0xffff0000, v79
	v_pk_mul_f32 v[6:7], v[82:83], v[0:1]
	v_pk_fma_f32 v[6:7], v[94:95], v[2:3], v[6:7]
	v_pk_fma_f32 v[6:7], v[98:99], v[4:5], v[6:7]
	v_pk_add_f32 v[6:7], v[110:111], v[6:7]
	v_lshlrev_b32_e32 v8, 16, v28
	v_lshlrev_b32_e32 v9, 16, v29
	v_pk_mul_f32 v[6:7], v[6:7], v[8:9]
	v_cvt_pk_bf16_f32 v127, v6, v7
	global_store_dwordx4 v[112:113], v[120:123], off
	global_store_dwordx4 v[114:115], v[124:127], off
	s_add_i32 s16, s20, s89
	s_add_i32 s10, s21, s11
	s_cmpk_lt_i32 s16, 0x800
	s_cbranch_scc0 .Lp2d_lastB
; #define LAS __attribute__((address_space(3)))
; DI int rot_t(int c, int t) { return (t + 128 * c) & (MTOK - 1); }
; DI void p2d_unit(const Frame& F, int unit, const bf16* HY, const bf16* YT, bf16* YH, const float* cw, const float* cb) {
;     ...
;     const int t0 = F.tid >> 3, cc = (F.tid & 7) * 8, c0 = cgp * 64 + cc;
;     u32x4 xa[2], xb[2], xc[2];
; #pragma unroll
;     for (int j = 0; j < 2; ++j) { const int tok = tt * 128 + t0 + 64 * j; bool hp, hn; tok_edges(tok, hp, hn); conv3_load(HY, tok, c0, hp, hn, xa[j], xb[j], xc[j]); }
;     { const int c = F.tid >> 3, cg = cgp * 64 + c;
; #pragma unroll
;       for (int j = 0; j < 2; ++j) { const int tch = (F.tid & 7) * 8 + 64 * j;
;           *(LAS u32x4*)(T + c * TR_ROW + tch * 2) = *(const u32x4*)(YT + (size_t)cg * MTOK + rot_t(cg, tt * 128 + tch)); } }
;     __syncthreads();
;     { ConvW W0; conv3_w(W0, cw, cb, c0);
; #pragma unroll
;       for (int j = 0; j < 2; ++j) { const int t = t0 + 64 * j, tok = tt * 128 + t; float x0[8], y[8]; conv3_do(W0, xa[j], xb[j], xc[j], x0);
; #pragma unroll
;           for (int e = 0; e < 8; ++e) y[e] = __uint_as_float((unsigned)(*(const LAS bf16*)(T + (cc + e) * TR_ROW + t * 2)) << 16) * x0[e];
	v_mov_b32_e32 v25, 0
	s_and_b32 s19, s10, 0x1c0
	s_ashr_i32 s18, s16, 3
	v_or_b32_e32 v30, s19, v35
	s_lshl_b32 s17, s18, 7
	v_lshlrev_b32_e32 v24, 1, v30
	v_or_b32_e32 v26, s17, v34
	v_add_u32_e32 v31, s19, v34
	v_lshlrev_b32_e32 v28, 16, v31
	v_add_lshl_u32 v31, v31, s18, 7
	v_mov_b32_e32 v29, v25
	v_and_or_b32 v31, v31, s15, v35
	v_lshl_add_u64 v[28:29], s[60:61], 0, v[28:29]
	v_lshlrev_b32_e32 v32, 1, v31
	v_mov_b32_e32 v33, v25
	v_lshl_add_u64 v[28:29], v[28:29], 0, v[32:33]
	global_load_dwordx4 v[48:51], v[28:29], off
	global_load_dwordx4 v[52:55], v[28:29], off offset:128
	v_lshl_add_u64 v[2:3], s[80:81], 0, v[24:25]
	v_mad_i64_i32 v[4:5], s[0:1], v26, s13, v[2:3]
	global_load_dwordx4 v[56:59], v[4:5], off
	v_bitop3_b32 v0, s17, v39, v34 bitop3:0xc8
	v_add_u32_e32 v1, 0xffffc000, v26
	v_cmp_gt_i32_e32 vcc, s12, v26
	v_mov_b32_e32 v60, 0
	v_mov_b32_e32 v61, 0
	v_mov_b32_e32 v62, 0
	v_mov_b32_e32 v63, 0
	v_cndmask_b32_e32 v0, v1, v0, vcc
	v_cmp_ne_u32_e64 s[0:1], 0, v0
	v_mov_b32_e32 v64, 0
	v_mov_b32_e32 v65, 0
	v_mov_b32_e32 v66, 0
	v_mov_b32_e32 v67, 0
	s_and_saveexec_b64 s[8:9], s[0:1]
	global_load_dwordx4 v[60:63], v[4:5], off offset:-3072
	s_or_b64 exec, exec, s[8:9]
	v_cndmask_b32_e32 v1, v40, v39, vcc
	v_cmp_lt_u32_e32 vcc, v0, v1
	s_and_saveexec_b64 s[0:1], vcc
	global_load_dwordx4 v[64:67], v[4:5], off offset:3072
	s_or_b64 exec, exec, s[0:1]
	v_add_u32_e32 v1, 64, v26
	v_mad_i64_i32 v[28:29], s[0:1], v1, s13, v[2:3]
	global_load_dwordx4 v[68:71], v[28:29], off
	v_and_b32_e32 v1, 0xfff, v1
	v_add_u32_e32 v2, 0xffffc040, v26
	v_cmp_gt_i32_e32 vcc, s14, v26
	v_mov_b32_e32 v72, 0
	v_mov_b32_e32 v73, 0
	v_mov_b32_e32 v74, 0
	v_mov_b32_e32 v75, 0
	v_cndmask_b32_e32 v8, v2, v1, vcc
	v_cmp_ne_u32_e64 s[0:1], 0, v8
	v_mov_b32_e32 v76, 0
	v_mov_b32_e32 v77, 0
	v_mov_b32_e32 v78, 0
	v_mov_b32_e32 v79, 0
	s_and_saveexec_b64 s[8:9], s[0:1]
	global_load_dwordx4 v[72:75], v[28:29], off offset:-3072
	s_or_b64 exec, exec, s[8:9]
	v_cndmask_b32_e32 v9, v40, v39, vcc
	v_cmp_lt_u32_e32 vcc, v8, v9
	s_and_saveexec_b64 s[0:1], vcc
	global_load_dwordx4 v[76:79], v[28:29], off offset:3072
	s_or_b64 exec, exec, s[0:1]
	v_lshlrev_b32_e32 v12, 2, v30
	v_lshl_add_u64 v[6:7], s[58:59], 0, v[24:25]
	v_ashrrev_i32_e32 v27, 31, v26
	global_load_dwordx4 v[80:83], v12, s[4:5] offset:16
	global_load_dwordx4 v[84:87], v12, s[4:5]
	global_load_dwordx4 v[88:91], v12, s[74:75]
	global_load_dwordx4 v[92:95], v12, s[74:75] offset:16
	global_load_dwordx4 v[96:99], v12, s[6:7] offset:16
	global_load_dwordx4 v[100:103], v12, s[6:7]
	global_load_dwordx4 v[104:107], v12, s[76:77]
	global_load_dwordx4 v[108:111], v12, s[76:77] offset:16
	v_lshlrev_b64 v[8:9], 10, v[26:27]
	v_lshl_add_u64 v[112:113], v[6:7], 0, v[8:9]
	v_add_u32_e32 v10, s17, v38
	v_ashrrev_i32_e32 v11, 31, v10
	v_lshlrev_b64 v[10:11], 10, v[10:11]
	v_lshl_add_u64 v[114:115], v[6:7], 0, v[10:11]
	s_waitcnt vmcnt(30)
	ds_write_b128 v44, v[170:173] offset:18432
	ds_write_b128 v41, v[174:177] offset:18432
	s_waitcnt lgkmcnt(0)
	s_barrier
	ds_read_u16 v14, v42 offset:18432
	ds_read_u16 v15, v42 offset:18704
	ds_read_u16 v16, v42 offset:18976
	ds_read_u16 v17, v42 offset:19248
	ds_read_u16 v18, v42 offset:19520
	ds_read_u16 v19, v42 offset:19792
	ds_read_u16 v20, v42 offset:20064
	ds_read_u16 v21, v42 offset:20336
	ds_read_u16 v22, v43 offset:18432
	ds_read_u16 v23, v43 offset:18704
	ds_read_u16 v24, v43 offset:18976
	ds_read_u16 v25, v43 offset:19248
	ds_read_u16 v26, v43 offset:19520
	ds_read_u16 v27, v43 offset:19792
	ds_read_u16 v28, v43 offset:20064
	ds_read_u16 v29, v43 offset:20336
	s_waitcnt vmcnt(16)
	v_lshlrev_b32_e32 v0, 16, v178
	v_and_b32_e32 v1, 0xffff0000, v178
	v_lshlrev_b32_e32 v2, 16, v182
	v_and_b32_e32 v3, 0xffff0000, v182
	v_lshlrev_b32_e32 v4, 16, v186
	v_and_b32_e32 v5, 0xffff0000, v186
	v_pk_mul_f32 v[6:7], v[206:207], v[0:1]
	v_pk_fma_f32 v[6:7], v[210:211], v[2:3], v[6:7]
	v_pk_fma_f32 v[6:7], v[222:223], v[4:5], v[6:7]
	v_pk_add_f32 v[6:7], v[226:227], v[6:7]
	s_waitcnt lgkmcnt(0)
	v_lshlrev_b32_e32 v8, 16, v14
	v_lshlrev_b32_e32 v9, 16, v15
	v_pk_mul_f32 v[6:7], v[6:7], v[8:9]
	v_cvt_pk_bf16_f32 v120, v6, v7
	v_lshlrev_b32_e32 v0, 16, v179
	v_and_b32_e32 v1, 0xffff0000, v179
	v_lshlrev_b32_e32 v2, 16, v183
	v_and_b32_e32 v3, 0xffff0000, v183
	v_lshlrev_b32_e32 v4, 16, v187
	v_and_b32_e32 v5, 0xffff0000, v187
	v_pk_mul_f32 v[6:7], v[208:209], v[0:1]
	v_pk_fma_f32 v[6:7], v[212:213], v[2:3], v[6:7]
	v_pk_fma_f32 v[6:7], v[224:225], v[4:5], v[6:7]
	v_pk_add_f32 v[6:7], v[228:229], v[6:7]
	v_lshlrev_b32_e32 v8, 16, v16
	v_lshlrev_b32_e32 v9, 16, v17
	v_pk_mul_f32 v[6:7], v[6:7], v[8:9]
	v_cvt_pk_bf16_f32 v121, v6, v7
	v_lshlrev_b32_e32 v0, 16, v180
	v_and_b32_e32 v1, 0xffff0000, v180
	v_lshlrev_b32_e32 v2, 16, v184
	v_and_b32_e32 v3, 0xffff0000, v184
	v_lshlrev_b32_e32 v4, 16, v188
	v_and_b32_e32 v5, 0xffff0000, v188
	v_pk_mul_f32 v[6:7], v[202:203], v[0:1]
	v_pk_fma_f32 v[6:7], v[214:215], v[2:3], v[6:7]
	v_pk_fma_f32 v[6:7], v[218:219], v[4:5], v[6:7]
	v_pk_add_f32 v[6:7], v[230:231], v[6:7]
	v_lshlrev_b32_e32 v8, 16, v18
	v_lshlrev_b32_e32 v9, 16, v19
	v_pk_mul_f32 v[6:7], v[6:7], v[8:9]
	v_cvt_pk_bf16_f32 v122, v6, v7
	v_lshlrev_b32_e32 v0, 16, v181
	v_and_b32_e32 v1, 0xffff0000, v181
	v_lshlrev_b32_e32 v2, 16, v185
	v_and_b32_e32 v3, 0xffff0000, v185
	v_lshlrev_b32_e32 v4, 16, v189
	v_and_b32_e32 v5, 0xffff0000, v189
	v_pk_mul_f32 v[6:7], v[204:205], v[0:1]
	v_pk_fma_f32 v[6:7], v[216:217], v[2:3], v[6:7]
	v_pk_fma_f32 v[6:7], v[220:221], v[4:5], v[6:7]
	v_pk_add_f32 v[6:7], v[232:233], v[6:7]
	v_lshlrev_b32_e32 v8, 16, v20
	v_lshlrev_b32_e32 v9, 16, v21
	v_pk_mul_f32 v[6:7], v[6:7], v[8:9]
; #define LAS __attribute__((address_space(3)))
; DI unsigned pk2(float lo, float hi) { f32x2_t v = {lo, hi}; bf16x2_t b = __builtin_convertvector(v, bf16x2_t); return __builtin_bit_cast(unsigned, b); }
; DI float bf_lo(unsigned w) { return __uint_as_float(w << 16); }
; DI float bf_hi(unsigned w) { return __uint_as_float(w & 0xffff0000u); }
; DI int rot_t(int c, int t) { return (t + 128 * c) & (MTOK - 1); }
; DI void conv3_do(const ConvW& W, const u32x4& a, const u32x4& b, const u32x4& c, float* o) {
; #pragma unroll
;     for (int d = 0; d < 4; ++d) {
;         o[2 * d]     = W.w0[2 * d] * bf_lo(a[d]) + W.w1[2 * d] * bf_lo(b[d]) + W.w2[2 * d] * bf_lo(c[d]) + W.bb[2 * d];
;         o[2 * d + 1] = W.w0[2 * d + 1] * bf_hi(a[d]) + W.w1[2 * d + 1] * bf_hi(b[d]) + W.w2[2 * d + 1] * bf_hi(c[d]) + W.bb[2 * d + 1];
;     }
; }
; DI void p2d_unit(const Frame& F, int unit, const bf16* HY, const bf16* YT, bf16* YH, const float* cw, const float* cb) {
;     ...
;     { const int c = F.tid >> 3, cg = cgp * 64 + c;
; #pragma unroll
;       for (int j = 0; j < 2; ++j) { const int tch = (F.tid & 7) * 8 + 64 * j;
;           *(LAS u32x4*)(T + c * TR_ROW + tch * 2) = *(const u32x4*)(YT + (size_t)cg * MTOK + rot_t(cg, tt * 128 + tch)); } }
;     __syncthreads();
;     { ConvW W0; conv3_w(W0, cw, cb, c0);
; #pragma unroll
;       for (int j = 0; j < 2; ++j) { const int t = t0 + 64 * j, tok = tt * 128 + t; float x0[8], y[8]; conv3_do(W0, xa[j], xb[j], xc[j], x0);
; #pragma unroll
;           for (int e = 0; e < 8; ++e) y[e] = __uint_as_float((unsigned)(*(const LAS bf16*)(T + (cc + e) * TR_ROW + t * 2)) << 16) * x0[e];
;           u32x4 w; w.x = pk2(y[0], y[1]); w.y = pk2(y[2], y[3]); w.z = pk2(y[4], y[5]); w.w = pk2(y[6], y[7]);
;           *(u32x4*)(YH + (size_t)tok * 512 + c0) = w; } }
	v_cvt_pk_bf16_f32 v123, v6, v7
	v_lshlrev_b32_e32 v0, 16, v190
	v_and_b32_e32 v1, 0xffff0000, v190
	v_lshlrev_b32_e32 v2, 16, v194
	v_and_b32_e32 v3, 0xffff0000, v194
	v_lshlrev_b32_e32 v4, 16, v198
	v_and_b32_e32 v5, 0xffff0000, v198
	v_pk_mul_f32 v[6:7], v[206:207], v[0:1]
	v_pk_fma_f32 v[6:7], v[210:211], v[2:3], v[6:7]
	v_pk_fma_f32 v[6:7], v[222:223], v[4:5], v[6:7]
	v_pk_add_f32 v[6:7], v[226:227], v[6:7]
	v_lshlrev_b32_e32 v8, 16, v22
	v_lshlrev_b32_e32 v9, 16, v23
	v_pk_mul_f32 v[6:7], v[6:7], v[8:9]
	v_cvt_pk_bf16_f32 v124, v6, v7
	v_lshlrev_b32_e32 v0, 16, v191
	v_and_b32_e32 v1, 0xffff0000, v191
	v_lshlrev_b32_e32 v2, 16, v195
	v_and_b32_e32 v3, 0xffff0000, v195
	v_lshlrev_b32_e32 v4, 16, v199
	v_and_b32_e32 v5, 0xffff0000, v199
	v_pk_mul_f32 v[6:7], v[208:209], v[0:1]
	v_pk_fma_f32 v[6:7], v[212:213], v[2:3], v[6:7]
	v_pk_fma_f32 v[6:7], v[224:225], v[4:5], v[6:7]
	v_pk_add_f32 v[6:7], v[228:229], v[6:7]
	v_lshlrev_b32_e32 v8, 16, v24
	v_lshlrev_b32_e32 v9, 16, v25
	v_pk_mul_f32 v[6:7], v[6:7], v[8:9]
	v_cvt_pk_bf16_f32 v125, v6, v7
	v_lshlrev_b32_e32 v0, 16, v192
	v_and_b32_e32 v1, 0xffff0000, v192
	v_lshlrev_b32_e32 v2, 16, v196
	v_and_b32_e32 v3, 0xffff0000, v196
	v_lshlrev_b32_e32 v4, 16, v200
	v_and_b32_e32 v5, 0xffff0000, v200
	v_pk_mul_f32 v[6:7], v[202:203], v[0:1]
	v_pk_fma_f32 v[6:7], v[214:215], v[2:3], v[6:7]
	v_pk_fma_f32 v[6:7], v[218:219], v[4:5], v[6:7]
	v_pk_add_f32 v[6:7], v[230:231], v[6:7]
	v_lshlrev_b32_e32 v8, 16, v26
	v_lshlrev_b32_e32 v9, 16, v27
	v_pk_mul_f32 v[6:7], v[6:7], v[8:9]
	v_cvt_pk_bf16_f32 v126, v6, v7
	v_lshlrev_b32_e32 v0, 16, v193
	v_and_b32_e32 v1, 0xffff0000, v193
	v_lshlrev_b32_e32 v2, 16, v197
	v_and_b32_e32 v3, 0xffff0000, v197
	v_lshlrev_b32_e32 v4, 16, v201
	v_and_b32_e32 v5, 0xffff0000, v201
	v_pk_mul_f32 v[6:7], v[204:205], v[0:1]
	v_pk_fma_f32 v[6:7], v[216:217], v[2:3], v[6:7]
	v_pk_fma_f32 v[6:7], v[220:221], v[4:5], v[6:7]
	v_pk_add_f32 v[6:7], v[232:233], v[6:7]
	v_lshlrev_b32_e32 v8, 16, v28
	v_lshlrev_b32_e32 v9, 16, v29
	v_pk_mul_f32 v[6:7], v[6:7], v[8:9]
	v_cvt_pk_bf16_f32 v127, v6, v7
	global_store_dwordx4 v[116:117], v[120:123], off
	global_store_dwordx4 v[118:119], v[124:127], off
	s_branch .Lp2d_loop
.Lp2d_lastA:
	s_waitcnt vmcnt(14)
	ds_write_b128 v44, v[48:51]
	ds_write_b128 v41, v[52:55]
	s_waitcnt lgkmcnt(0)
	s_barrier
	ds_read_u16 v14, v42
	ds_read_u16 v15, v42 offset:272
	ds_read_u16 v16, v42 offset:544
	ds_read_u16 v17, v42 offset:816
	ds_read_u16 v18, v42 offset:1088
	ds_read_u16 v19, v42 offset:1360
	ds_read_u16 v20, v42 offset:1632
	ds_read_u16 v21, v42 offset:1904
	ds_read_u16 v22, v43
	ds_read_u16 v23, v43 offset:272
	ds_read_u16 v24, v43 offset:544
	ds_read_u16 v25, v43 offset:816
	ds_read_u16 v26, v43 offset:1088
	ds_read_u16 v27, v43 offset:1360
	ds_read_u16 v28, v43 offset:1632
	ds_read_u16 v29, v43 offset:1904
	s_waitcnt vmcnt(0)
	v_lshlrev_b32_e32 v0, 16, v56
	v_and_b32_e32 v1, 0xffff0000, v56
	v_lshlrev_b32_e32 v2, 16, v60
	v_and_b32_e32 v3, 0xffff0000, v60
	v_lshlrev_b32_e32 v4, 16, v64
	v_and_b32_e32 v5, 0xffff0000, v64
	v_pk_mul_f32 v[6:7], v[84:85], v[0:1]
	v_pk_fma_f32 v[6:7], v[88:89], v[2:3], v[6:7]
	v_pk_fma_f32 v[6:7], v[100:101], v[4:5], v[6:7]
	v_pk_add_f32 v[6:7], v[104:105], v[6:7]
	s_waitcnt lgkmcnt(0)
	v_lshlrev_b32_e32 v8, 16, v14
	v_lshlrev_b32_e32 v9, 16, v15
	v_pk_mul_f32 v[6:7], v[6:7], v[8:9]
	v_cvt_pk_bf16_f32 v120, v6, v7
	v_lshlrev_b32_e32 v0, 16, v57
	v_and_b32_e32 v1, 0xffff0000, v57
	v_lshlrev_b32_e32 v2, 16, v61
	v_and_b32_e32 v3, 0xffff0000, v61
	v_lshlrev_b32_e32 v4, 16, v65
	v_and_b32_e32 v5, 0xffff0000, v65
	v_pk_mul_f32 v[6:7], v[86:87], v[0:1]
	v_pk_fma_f32 v[6:7], v[90:91], v[2:3], v[6:7]
	v_pk_fma_f32 v[6:7], v[102:103], v[4:5], v[6:7]
	v_pk_add_f32 v[6:7], v[106:107], v[6:7]
	v_lshlrev_b32_e32 v8, 16, v16
	v_lshlrev_b32_e32 v9, 16, v17
	v_pk_mul_f32 v[6:7], v[6:7], v[8:9]
	v_cvt_pk_bf16_f32 v121, v6, v7
	v_lshlrev_b32_e32 v0, 16, v58
	v_and_b32_e32 v1, 0xffff0000, v58
	v_lshlrev_b32_e32 v2, 16, v62
	v_and_b32_e32 v3, 0xffff0000, v62
	v_lshlrev_b32_e32 v4, 16, v66
	v_and_b32_e32 v5, 0xffff0000, v66
	v_pk_mul_f32 v[6:7], v[80:81], v[0:1]
	v_pk_fma_f32 v[6:7], v[92:93], v[2:3], v[6:7]
	v_pk_fma_f32 v[6:7], v[96:97], v[4:5], v[6:7]
	v_pk_add_f32 v[6:7], v[108:109], v[6:7]
	v_lshlrev_b32_e32 v8, 16, v18
	v_lshlrev_b32_e32 v9, 16, v19
	v_pk_mul_f32 v[6:7], v[6:7], v[8:9]
	v_cvt_pk_bf16_f32 v122, v6, v7
	v_lshlrev_b32_e32 v0, 16, v59
	v_and_b32_e32 v1, 0xffff0000, v59
	v_lshlrev_b32_e32 v2, 16, v63
	v_and_b32_e32 v3, 0xffff0000, v63
	v_lshlrev_b32_e32 v4, 16, v67
	v_and_b32_e32 v5, 0xffff0000, v67
	v_pk_mul_f32 v[6:7], v[82:83], v[0:1]
	v_pk_fma_f32 v[6:7], v[94:95], v[2:3], v[6:7]
	v_pk_fma_f32 v[6:7], v[98:99], v[4:5], v[6:7]
	v_pk_add_f32 v[6:7], v[110:111], v[6:7]
	v_lshlrev_b32_e32 v8, 16, v20
	v_lshlrev_b32_e32 v9, 16, v21
	v_pk_mul_f32 v[6:7], v[6:7], v[8:9]
	v_cvt_pk_bf16_f32 v123, v6, v7
	v_lshlrev_b32_e32 v0, 16, v68
	v_and_b32_e32 v1, 0xffff0000, v68
	v_lshlrev_b32_e32 v2, 16, v72
	v_and_b32_e32 v3, 0xffff0000, v72
	v_lshlrev_b32_e32 v4, 16, v76
	v_and_b32_e32 v5, 0xffff0000, v76
	v_pk_mul_f32 v[6:7], v[84:85], v[0:1]
	v_pk_fma_f32 v[6:7], v[88:89], v[2:3], v[6:7]
	v_pk_fma_f32 v[6:7], v[100:101], v[4:5], v[6:7]
	v_pk_add_f32 v[6:7], v[104:105], v[6:7]
	v_lshlrev_b32_e32 v8, 16, v22
	v_lshlrev_b32_e32 v9, 16, v23
	v_pk_mul_f32 v[6:7], v[6:7], v[8:9]
	v_cvt_pk_bf16_f32 v124, v6, v7
	v_lshlrev_b32_e32 v0, 16, v69
	v_and_b32_e32 v1, 0xffff0000, v69
	v_lshlrev_b32_e32 v2, 16, v73
	v_and_b32_e32 v3, 0xffff0000, v73
	v_lshlrev_b32_e32 v4, 16, v77
	v_and_b32_e32 v5, 0xffff0000, v77
	v_pk_mul_f32 v[6:7], v[86:87], v[0:1]
	v_pk_fma_f32 v[6:7], v[90:91], v[2:3], v[6:7]
	v_pk_fma_f32 v[6:7], v[102:103], v[4:5], v[6:7]
	v_pk_add_f32 v[6:7], v[106:107], v[6:7]
	v_lshlrev_b32_e32 v8, 16, v24
	v_lshlrev_b32_e32 v9, 16, v25
	v_pk_mul_f32 v[6:7], v[6:7], v[8:9]
	v_cvt_pk_bf16_f32 v125, v6, v7
	v_lshlrev_b32_e32 v0, 16, v70
	v_and_b32_e32 v1, 0xffff0000, v70
	v_lshlrev_b32_e32 v2, 16, v74
	v_and_b32_e32 v3, 0xffff0000, v74
	v_lshlrev_b32_e32 v4, 16, v78
	v_and_b32_e32 v5, 0xffff0000, v78
	v_pk_mul_f32 v[6:7], v[80:81], v[0:1]
	v_pk_fma_f32 v[6:7], v[92:93], v[2:3], v[6:7]
	v_pk_fma_f32 v[6:7], v[96:97], v[4:5], v[6:7]
	v_pk_add_f32 v[6:7], v[108:109], v[6:7]
	v_lshlrev_b32_e32 v8, 16, v26
	v_lshlrev_b32_e32 v9, 16, v27
	v_pk_mul_f32 v[6:7], v[6:7], v[8:9]
	v_cvt_pk_bf16_f32 v126, v6, v7
	v_lshlrev_b32_e32 v0, 16, v71
	v_and_b32_e32 v1, 0xffff0000, v71
	v_lshlrev_b32_e32 v2, 16, v75
	v_and_b32_e32 v3, 0xffff0000, v75
	v_lshlrev_b32_e32 v4, 16, v79
	v_and_b32_e32 v5, 0xffff0000, v79
	v_pk_mul_f32 v[6:7], v[82:83], v[0:1]
	v_pk_fma_f32 v[6:7], v[94:95], v[2:3], v[6:7]
	v_pk_fma_f32 v[6:7], v[98:99], v[4:5], v[6:7]
	v_pk_add_f32 v[6:7], v[110:111], v[6:7]
	v_lshlrev_b32_e32 v8, 16, v28
	v_lshlrev_b32_e32 v9, 16, v29
	v_pk_mul_f32 v[6:7], v[6:7], v[8:9]
	v_cvt_pk_bf16_f32 v127, v6, v7
	global_store_dwordx4 v[112:113], v[120:123], off
	global_store_dwordx4 v[114:115], v[124:127], off
	s_branch .Lp2d_end
; #define LAS __attribute__((address_space(3)))
; DI unsigned pk2(float lo, float hi) { f32x2_t v = {lo, hi}; bf16x2_t b = __builtin_convertvector(v, bf16x2_t); return __builtin_bit_cast(unsigned, b); }
; DI int rot_t(int c, int t) { return (t + 128 * c) & (MTOK - 1); }
; DI void p2d_unit(const Frame& F, int unit, const bf16* HY, const bf16* YT, bf16* YH, const float* cw, const float* cb) {
;     ...
;     { const int c = F.tid >> 3, cg = cgp * 64 + c;
; #pragma unroll
;       for (int j = 0; j < 2; ++j) { const int tch = (F.tid & 7) * 8 + 64 * j;
;           *(LAS u32x4*)(T + c * TR_ROW + tch * 2) = *(const u32x4*)(YT + (size_t)cg * MTOK + rot_t(cg, tt * 128 + tch)); } }
;     __syncthreads();
;     { ConvW W0; conv3_w(W0, cw, cb, c0);
; #pragma unroll
;       for (int j = 0; j < 2; ++j) { const int t = t0 + 64 * j, tok = tt * 128 + t; float x0[8], y[8]; conv3_do(W0, xa[j], xb[j], xc[j], x0);
; #pragma unroll
;           for (int e = 0; e < 8; ++e) y[e] = __uint_as_float((unsigned)(*(const LAS bf16*)(T + (cc + e) * TR_ROW + t * 2)) << 16) * x0[e];
;           u32x4 w; w.x = pk2(y[0], y[1]); w.y = pk2(y[2], y[3]); w.z = pk2(y[4], y[5]); w.w = pk2(y[6], y[7]);
;           *(u32x4*)(YH + (size_t)tok * 512 + c0) = w; } }
;     __syncthreads();
.Lp2d_lastB:
	s_waitcnt vmcnt(14)
	ds_write_b128 v44, v[170:173] offset:18432
	ds_write_b128 v41, v[174:177] offset:18432
	s_waitcnt lgkmcnt(0)
	s_barrier
	ds_read_u16 v14, v42 offset:18432
	ds_read_u16 v15, v42 offset:18704
	ds_read_u16 v16, v42 offset:18976
	ds_read_u16 v17, v42 offset:19248
	ds_read_u16 v18, v42 offset:19520
	ds_read_u16 v19, v42 offset:19792
	ds_read_u16 v20, v42 offset:20064
	ds_read_u16 v21, v42 offset:20336
	ds_read_u16 v22, v43 offset:18432
	ds_read_u16 v23, v43 offset:18704
	ds_read_u16 v24, v43 offset:18976
	ds_read_u16 v25, v43 offset:19248
	ds_read_u16 v26, v43 offset:19520
	ds_read_u16 v27, v43 offset:19792
	ds_read_u16 v28, v43 offset:20064
	ds_read_u16 v29, v43 offset:20336
	s_waitcnt vmcnt(0)
	v_lshlrev_b32_e32 v0, 16, v178
	v_and_b32_e32 v1, 0xffff0000, v178
	v_lshlrev_b32_e32 v2, 16, v182
	v_and_b32_e32 v3, 0xffff0000, v182
	v_lshlrev_b32_e32 v4, 16, v186
	v_and_b32_e32 v5, 0xffff0000, v186
	v_pk_mul_f32 v[6:7], v[206:207], v[0:1]
	v_pk_fma_f32 v[6:7], v[210:211], v[2:3], v[6:7]
	v_pk_fma_f32 v[6:7], v[222:223], v[4:5], v[6:7]
	v_pk_add_f32 v[6:7], v[226:227], v[6:7]
	s_waitcnt lgkmcnt(0)
	v_lshlrev_b32_e32 v8, 16, v14
	v_lshlrev_b32_e32 v9, 16, v15
	v_pk_mul_f32 v[6:7], v[6:7], v[8:9]
	v_cvt_pk_bf16_f32 v120, v6, v7
	v_lshlrev_b32_e32 v0, 16, v179
	v_and_b32_e32 v1, 0xffff0000, v179
	v_lshlrev_b32_e32 v2, 16, v183
	v_and_b32_e32 v3, 0xffff0000, v183
	v_lshlrev_b32_e32 v4, 16, v187
	v_and_b32_e32 v5, 0xffff0000, v187
	v_pk_mul_f32 v[6:7], v[208:209], v[0:1]
	v_pk_fma_f32 v[6:7], v[212:213], v[2:3], v[6:7]
	v_pk_fma_f32 v[6:7], v[224:225], v[4:5], v[6:7]
	v_pk_add_f32 v[6:7], v[228:229], v[6:7]
	v_lshlrev_b32_e32 v8, 16, v16
	v_lshlrev_b32_e32 v9, 16, v17
	v_pk_mul_f32 v[6:7], v[6:7], v[8:9]
	v_cvt_pk_bf16_f32 v121, v6, v7
	v_lshlrev_b32_e32 v0, 16, v180
	v_and_b32_e32 v1, 0xffff0000, v180
	v_lshlrev_b32_e32 v2, 16, v184
	v_and_b32_e32 v3, 0xffff0000, v184
	v_lshlrev_b32_e32 v4, 16, v188
	v_and_b32_e32 v5, 0xffff0000, v188
	v_pk_mul_f32 v[6:7], v[202:203], v[0:1]
	v_pk_fma_f32 v[6:7], v[214:215], v[2:3], v[6:7]
	v_pk_fma_f32 v[6:7], v[218:219], v[4:5], v[6:7]
	v_pk_add_f32 v[6:7], v[230:231], v[6:7]
	v_lshlrev_b32_e32 v8, 16, v18
	v_lshlrev_b32_e32 v9, 16, v19
	v_pk_mul_f32 v[6:7], v[6:7], v[8:9]
	v_cvt_pk_bf16_f32 v122, v6, v7
	v_lshlrev_b32_e32 v0, 16, v181
	v_and_b32_e32 v1, 0xffff0000, v181
	v_lshlrev_b32_e32 v2, 16, v185
	v_and_b32_e32 v3, 0xffff0000, v185
	v_lshlrev_b32_e32 v4, 16, v189
	v_and_b32_e32 v5, 0xffff0000, v189
	v_pk_mul_f32 v[6:7], v[204:205], v[0:1]
	v_pk_fma_f32 v[6:7], v[216:217], v[2:3], v[6:7]
	v_pk_fma_f32 v[6:7], v[220:221], v[4:5], v[6:7]
	v_pk_add_f32 v[6:7], v[232:233], v[6:7]
	v_lshlrev_b32_e32 v8, 16, v20
	v_lshlrev_b32_e32 v9, 16, v21
	v_pk_mul_f32 v[6:7], v[6:7], v[8:9]
	v_cvt_pk_bf16_f32 v123, v6, v7
	v_lshlrev_b32_e32 v0, 16, v190
	v_and_b32_e32 v1, 0xffff0000, v190
	v_lshlrev_b32_e32 v2, 16, v194
	v_and_b32_e32 v3, 0xffff0000, v194
	v_lshlrev_b32_e32 v4, 16, v198
	v_and_b32_e32 v5, 0xffff0000, v198
	v_pk_mul_f32 v[6:7], v[206:207], v[0:1]
	v_pk_fma_f32 v[6:7], v[210:211], v[2:3], v[6:7]
	v_pk_fma_f32 v[6:7], v[222:223], v[4:5], v[6:7]
	v_pk_add_f32 v[6:7], v[226:227], v[6:7]
	v_lshlrev_b32_e32 v8, 16, v22
	v_lshlrev_b32_e32 v9, 16, v23
	v_pk_mul_f32 v[6:7], v[6:7], v[8:9]
	v_cvt_pk_bf16_f32 v124, v6, v7
	v_lshlrev_b32_e32 v0, 16, v191
	v_and_b32_e32 v1, 0xffff0000, v191
	v_lshlrev_b32_e32 v2, 16, v195
	v_and_b32_e32 v3, 0xffff0000, v195
	v_lshlrev_b32_e32 v4, 16, v199
	v_and_b32_e32 v5, 0xffff0000, v199
	v_pk_mul_f32 v[6:7], v[208:209], v[0:1]
	v_pk_fma_f32 v[6:7], v[212:213], v[2:3], v[6:7]
	v_pk_fma_f32 v[6:7], v[224:225], v[4:5], v[6:7]
	v_pk_add_f32 v[6:7], v[228:229], v[6:7]
	v_lshlrev_b32_e32 v8, 16, v24
	v_lshlrev_b32_e32 v9, 16, v25
	v_pk_mul_f32 v[6:7], v[6:7], v[8:9]
	v_cvt_pk_bf16_f32 v125, v6, v7
	v_lshlrev_b32_e32 v0, 16, v192
	v_and_b32_e32 v1, 0xffff0000, v192
	v_lshlrev_b32_e32 v2, 16, v196
	v_and_b32_e32 v3, 0xffff0000, v196
	v_lshlrev_b32_e32 v4, 16, v200
	v_and_b32_e32 v5, 0xffff0000, v200
	v_pk_mul_f32 v[6:7], v[202:203], v[0:1]
	v_pk_fma_f32 v[6:7], v[214:215], v[2:3], v[6:7]
	v_pk_fma_f32 v[6:7], v[218:219], v[4:5], v[6:7]
	v_pk_add_f32 v[6:7], v[230:231], v[6:7]
	v_lshlrev_b32_e32 v8, 16, v26
	v_lshlrev_b32_e32 v9, 16, v27
	v_pk_mul_f32 v[6:7], v[6:7], v[8:9]
	v_cvt_pk_bf16_f32 v126, v6, v7
	v_lshlrev_b32_e32 v0, 16, v193
	v_and_b32_e32 v1, 0xffff0000, v193
	v_lshlrev_b32_e32 v2, 16, v197
	v_and_b32_e32 v3, 0xffff0000, v197
	v_lshlrev_b32_e32 v4, 16, v201
	v_and_b32_e32 v5, 0xffff0000, v201
	v_pk_mul_f32 v[6:7], v[204:205], v[0:1]
	v_pk_fma_f32 v[6:7], v[216:217], v[2:3], v[6:7]
	v_pk_fma_f32 v[6:7], v[220:221], v[4:5], v[6:7]
	v_pk_add_f32 v[6:7], v[232:233], v[6:7]
	v_lshlrev_b32_e32 v8, 16, v28
	v_lshlrev_b32_e32 v9, 16, v29
	v_pk_mul_f32 v[6:7], v[6:7], v[8:9]
	v_cvt_pk_bf16_f32 v127, v6, v7
	global_store_dwordx4 v[116:117], v[120:123], off
	global_store_dwordx4 v[118:119], v[124:127], off
.Lp2d_end:
	s_nop 0
	s_nop 0
	s_nop 0
	s_nop 0
	s_barrier
